# P5 residual epilogue: each block touches the next block's X rows (L2 prefetch) with dead registers
# baseline (speedup 1.0000x reference)
;     __device__ __forceinline__ void operator()(const AccT& acc, const pg8::Unit& u, int wr, int wc, int fr, int fq) const {
;         const int row0 = u.pm * 256 + wr * 64 + fr, col0 = u.pn * 256 + wc * 32 + 8 * fq;
;         f32x4 g0[2], g1[2];
; #pragma unroll
;         for (int bj = 0; bj < 2; ++bj) { g0[bj] = *(const f32x4*)(gn + col0 + bj * 128); g1[bj] = *(const f32x4*)(gn + col0 + bj * 128 + 4); }
; #pragma unroll
;         for (int ai = 0; ai < 2; ++ai)
; #pragma unroll
;             for (int mh = 0; mh < 2; ++mh) {
;                 f32x4 x0[4], x1[4];
; #pragma unroll
;                 for (int q = 0; q < 4; ++q) { const int m = 2 * mh + (q >> 1), bj = q & 1; const size_t o = (size_t)(row0 + ai * 128 + m * 16) * D + col0 + bj * 128;
;                     x0[q] = __builtin_nontemporal_load((const f32x4*)(X + o)); x1[q] = __builtin_nontemporal_load((const f32x4*)(X + o + 4)); }
.LBB0_611:
	v_lshl_or_b32 v160, s60, 8, v170
	v_ashrrev_i32_e32 v161, 31, v160
	v_lshl_add_u32 v162, s61, 8, v168
	v_readlane_b32 s64, v235, 5
	v_lshlrev_b64 v[96:97], 2, v[160:161]
	v_readlane_b32 s65, v235, 6
	v_ashrrev_i32_e32 v163, 31, v162
	v_readlane_b32 s66, v235, 7
	v_readlane_b32 s67, v235, 8
	v_readlane_b32 s68, v235, 9
	v_readlane_b32 s69, v235, 10
	v_readlane_b32 s70, v235, 11
	v_readlane_b32 s71, v235, 12
	v_readlane_b32 s72, v235, 13
	v_readlane_b32 s73, v235, 14
	v_readlane_b32 s74, v235, 15
	v_readlane_b32 s75, v235, 16
	v_readlane_b32 s76, v235, 17
	v_readlane_b32 s77, v235, 18
	v_readlane_b32 s78, v235, 19
	v_readlane_b32 s79, v235, 20
	v_lshl_add_u64 v[164:165], s[64:65], 0, v[96:97]
	v_lshlrev_b64 v[98:99], 13, v[162:163]
	v_lshl_add_u64 v[98:99], v[164:165], 0, v[98:99]
	v_readlane_b32 s64, v235, 21
	global_load_dwordx4 v[178:181], v[98:99], off nt
	global_load_dwordx4 v[182:185], v[98:99], off offset:16 nt
	global_load_dwordx4 v[186:189], v[98:99], off offset:512 nt
	global_load_dwordx4 v[190:193], v[98:99], off offset:528 nt
	v_readlane_b32 s74, v235, 31
	v_readlane_b32 s75, v235, 32
	v_or_b32_e32 v166, 16, v162
	v_ashrrev_i32_e32 v167, 31, v166
	v_lshl_add_u64 v[96:97], s[74:75], 0, v[96:97]
	global_load_dwordx4 v[124:127], v[96:97], off
	global_load_dwordx4 v[120:123], v[96:97], off offset:16
	global_load_dwordx4 v[108:111], v[96:97], off offset:512
	s_nop 0
	global_load_dwordx4 v[96:99], v[96:97], off offset:528
	v_lshlrev_b64 v[176:177], 13, v[166:167]
	v_lshl_add_u64 v[206:207], v[164:165], 0, v[176:177]
	global_load_dwordx4 v[194:197], v[206:207], off nt
	global_load_dwordx4 v[198:201], v[206:207], off offset:16 nt
	global_load_dwordx4 v[202:205], v[206:207], off offset:528 nt
	s_nop 0
	global_load_dwordx4 v[206:209], v[206:207], off offset:512 nt
	v_or_b32_e32 v224, 32, v162
	v_ashrrev_i32_e32 v225, 31, v224
	v_lshlrev_b64 v[224:225], 13, v[224:225]
	v_lshl_add_u64 v[224:225], v[164:165], 0, v[224:225]
	global_load_dword v228, v[224:225], off
	global_load_dword v228, v[224:225], off offset:512
	v_or_b32_e32 v226, 48, v162
	v_ashrrev_i32_e32 v227, 31, v226
	v_lshlrev_b64 v[226:227], 13, v[226:227]
	v_lshl_add_u64 v[226:227], v[164:165], 0, v[226:227]
	global_load_dword v228, v[226:227], off
	global_load_dword v228, v[226:227], off offset:512
	v_and_b32_e32 v176, 64, v174
	v_xor_b32_e32 v175, 16, v174
	v_add_u32_e32 v176, 64, v176
	v_xor_b32_e32 v177, 32, v174
	v_cmp_lt_i32_e32 vcc, v175, v176
	v_lshlrev_b64 v[210:211], 11, v[162:163]
	v_lshl_add_u64 v[210:211], v[210:211], 0, v[160:161]
	v_cndmask_b32_e32 v175, v174, v175, vcc
	v_cmp_lt_i32_e32 vcc, v177, v176
	v_lshl_add_u64 v[212:213], v[210:211], 2, s[48:49]
	v_lshlrev_b32_e32 v176, 2, v175
	v_cndmask_b32_e32 v177, v174, v177, vcc
	v_lshlrev_b32_e32 v175, 2, v177
	v_lshlrev_b64 v[210:211], 1, v[210:211]
	v_lshl_add_u64 v[216:217], s[42:43], 0, v[210:211]
	v_or_b32_e32 v210, 0x100, v210
	s_lshl_b32 s18, s60, 2
	s_ashr_i32 s19, s18, 31
	s_lshl_b64 s[18:19], s[18:19], 2
	s_add_u32 s18, s34, s18
	s_addc_u32 s19, s35, s19
	v_readlane_b32 s65, v235, 22
	v_readlane_b32 s66, v235, 23
	v_readlane_b32 s67, v235, 24
	v_readlane_b32 s68, v235, 25
	v_readlane_b32 s69, v235, 26
	v_readlane_b32 s70, v235, 27
	v_readlane_b32 s71, v235, 28
	v_readlane_b32 s72, v235, 29
	v_readlane_b32 s73, v235, 30
	v_readlane_b32 s76, v235, 33
	v_readlane_b32 s77, v235, 34
	v_readlane_b32 s78, v235, 35
	v_readlane_b32 s79, v235, 36
	s_waitcnt vmcnt(0)
; __device__ __forceinline__ unsigned pk2(float lo, float hi) { f32x2 v = {lo, hi}; bf16x2_t b = __builtin_convertvector(v, bf16x2_t); return __builtin_bit_cast(unsigned, b); }
;     __device__ __forceinline__ void operator()(const AccT& acc, const pg8::Unit& u, int wr, int wc, int fr, int fq) const {
;     ...
;                 float ss[2] = {0.f, 0.f};
; #pragma unroll
;                 for (int q = 0; q < 4; ++q) { const int m = 2 * mh + (q >> 1), bj = q & 1; const size_t o = (size_t)(row0 + ai * 128 + m * 16) * D + col0 + bj * 128;
;                     const f32x4 h0 = x0[q] + acc[ai][bj][m][0], h1 = x1[q] + acc[ai][bj][m][1];
;                     *(f32x4*)(H + o) = h0; *(f32x4*)(H + o + 4) = h1;
;                     ss[q >> 1] += (h0.x * h0.x + h0.y * h0.y) + (h0.z * h0.z + h0.w * h0.w) + (h1.x * h1.x + h1.y * h1.y) + (h1.z * h1.z + h1.w * h1.w);
;                     const f32x4 f0 = h0 * g0[bj], f1 = h1 * g1[bj];
;                     u32x4 w; w.x = pk2(f0.x, f0.y); w.y = pk2(f0.z, f0.w); w.z = pk2(f1.x, f1.y); w.w = pk2(f1.z, f1.w);
;                     *(u32x4*)(Fu + o) = w; }
; #pragma unroll
;                 for (int mm = 0; mm < 2; ++mm) { float v = ss[mm]; v += __shfl_xor(v, 16); v += __shfl_xor(v, 32);
;                     if (fq == 0) SSP[(size_t)(row0 + ai * 128 + (2 * mh + mm) * 16) * 32 + u.pn * 4 + wc] = v; }
	v_pk_add_f32 v[138:139], v[138:139], v[180:181]
	v_pk_add_f32 v[136:137], v[136:137], v[178:179]
	v_pk_add_f32 v[142:143], v[142:143], v[184:185]
	v_pk_add_f32 v[140:141], v[140:141], v[182:183]
	v_pk_add_f32 v[134:135], v[134:135], v[188:189]
	v_pk_add_f32 v[132:133], v[132:133], v[186:187]
	v_pk_add_f32 v[128:129], v[128:129], v[190:191]
	global_store_dwordx4 v[212:213], v[136:139], off
	global_store_dwordx4 v[212:213], v[140:143], off offset:16
	v_mul_f32_e32 v177, v137, v137
	v_mul_f32_e32 v218, v139, v139
	v_mul_f32_e32 v220, v143, v143
	v_pk_mul_f32 v[178:179], v[126:127], v[138:139]
	v_pk_mul_f32 v[180:181], v[124:125], v[136:137]
	v_pk_mul_f32 v[182:183], v[122:123], v[142:143]
	v_pk_mul_f32 v[184:185], v[120:121], v[140:141]
	v_mul_f32_e32 v143, v133, v133
	v_mul_f32_e32 v221, v135, v135
	v_pk_add_f32 v[130:131], v[130:131], v[192:193]
	v_mul_f32_e32 v219, v141, v141
	v_mul_f32_e32 v222, v129, v129
	v_fmac_f32_e32 v177, v136, v136
	v_fmac_f32_e32 v218, v138, v138
	v_cvt_pk_bf16_f32 v136, v180, v181
	v_cvt_pk_bf16_f32 v137, v178, v179
	v_cvt_pk_bf16_f32 v138, v184, v185
	v_cvt_pk_bf16_f32 v139, v182, v183
	v_fmac_f32_e32 v143, v132, v132
	v_fmac_f32_e32 v221, v134, v134
	v_mul_f32_e32 v223, v131, v131
	v_pk_mul_f32 v[192:193], v[96:97], v[128:129]
	v_fmac_f32_e32 v219, v140, v140
	v_fmac_f32_e32 v220, v142, v142
	v_fmac_f32_e32 v222, v128, v128
	v_add_f32_e32 v142, v177, v218
	global_store_dwordx4 v[216:217], v[136:139], off
	global_store_dwordx4 v[212:213], v[132:135], off offset:512
	global_store_dwordx4 v[212:213], v[128:131], off offset:528
	v_fmac_f32_e32 v223, v130, v130
	v_pk_mul_f32 v[186:187], v[110:111], v[134:135]
	v_add_f32_e32 v128, v143, v221
	v_add_f32_e32 v129, v142, v219
	v_add_f32_e32 v128, v128, v222
	v_pk_mul_f32 v[188:189], v[108:109], v[132:133]
	v_pk_mul_f32 v[190:191], v[98:99], v[130:131]
	v_add_f32_e32 v129, v220, v129
	v_add_f32_e32 v128, v223, v128
	v_cvt_pk_bf16_f32 v140, v188, v189
	v_cvt_pk_bf16_f32 v141, v186, v187
	v_add_f32_e32 v177, v129, v128
	v_cvt_pk_bf16_f32 v142, v192, v193
	v_cvt_pk_bf16_f32 v143, v190, v191
	v_lshl_add_u64 v[128:129], s[42:43], 0, v[210:211]
	global_store_dwordx4 v[128:129], v[140:143], off
	v_lshlrev_b64 v[128:129], 11, v[166:167]
	v_pk_add_f32 v[118:119], v[118:119], v[196:197]
	v_pk_add_f32 v[116:117], v[116:117], v[194:195]
	v_pk_add_f32 v[114:115], v[114:115], v[200:201]
	v_lshl_add_u64 v[132:133], v[128:129], 0, v[160:161]
	v_pk_add_f32 v[112:113], v[112:113], v[198:199]
	v_pk_mul_f32 v[130:131], v[126:127], v[118:119]
	v_pk_mul_f32 v[128:129], v[124:125], v[116:117]
	v_pk_mul_f32 v[136:137], v[122:123], v[114:115]
	v_pk_mul_f32 v[138:139], v[120:121], v[112:113]
	v_cvt_pk_bf16_f32 v128, v128, v129
	v_cvt_pk_bf16_f32 v129, v130, v131
	v_cvt_pk_bf16_f32 v131, v136, v137
	v_lshlrev_b64 v[136:137], 1, v[132:133]
	v_lshl_add_u64 v[134:135], v[132:133], 2, s[48:49]
	v_cvt_pk_bf16_f32 v130, v138, v139
	v_lshl_add_u64 v[132:133], s[42:43], 0, v[136:137]
	v_pk_add_f32 v[106:107], v[106:107], v[208:209]
	v_pk_add_f32 v[104:105], v[104:105], v[206:207]
	global_store_dwordx4 v[134:135], v[116:119], off
	global_store_dwordx4 v[134:135], v[112:115], off offset:16
	global_store_dwordx4 v[132:133], v[128:131], off
	v_pk_add_f32 v[102:103], v[102:103], v[204:205]
	v_pk_add_f32 v[100:101], v[100:101], v[202:203]
	v_pk_mul_f32 v[128:129], v[110:111], v[106:107]
	v_pk_mul_f32 v[130:131], v[108:109], v[104:105]
	global_store_dwordx4 v[134:135], v[104:107], off offset:512
	global_store_dwordx4 v[134:135], v[100:103], off offset:528
	v_cvt_pk_bf16_f32 v130, v130, v131
	v_cvt_pk_bf16_f32 v131, v128, v129
	ds_bpermute_b32 v128, v176, v177
	v_pk_mul_f32 v[134:135], v[98:99], v[102:103]
	v_pk_mul_f32 v[132:133], v[96:97], v[100:101]
	v_or_b32_e32 v136, 0x100, v136
	v_cvt_pk_bf16_f32 v132, v132, v133
	s_waitcnt lgkmcnt(0)
	v_add_f32_e32 v128, v177, v128
	ds_bpermute_b32 v129, v175, v128
	v_cvt_pk_bf16_f32 v133, v134, v135
	v_lshl_add_u64 v[134:135], s[42:43], 0, v[136:137]
	global_store_dwordx4 v[134:135], v[130:133], off
	s_and_saveexec_b64 s[20:21], s[6:7]
	s_cbranch_execz .LBB0_613
	s_waitcnt lgkmcnt(0)
	v_add_f32_e32 v130, v128, v129
	v_lshlrev_b64 v[128:129], 7, v[162:163]
	v_lshl_add_u64 v[128:129], s[18:19], 0, v[128:129]
	global_store_dword v[128:129], v130, off

; __device__ __forceinline__ unsigned pk2(float lo, float hi) { f32x2 v = {lo, hi}; bf16x2_t b = __builtin_convertvector(v, bf16x2_t); return __builtin_bit_cast(unsigned, b); }
;     __device__ __forceinline__ void operator()(const AccT& acc, const pg8::Unit& u, int wr, int wc, int fr, int fq) const {
;     ...
;             for (int mh = 0; mh < 2; ++mh) {
;                 f32x4 x0[4], x1[4];
; #pragma unroll
;                 for (int q = 0; q < 4; ++q) { const int m = 2 * mh + (q >> 1), bj = q & 1; const size_t o = (size_t)(row0 + ai * 128 + m * 16) * D + col0 + bj * 128;
;                     x0[q] = __builtin_nontemporal_load((const f32x4*)(X + o)); x1[q] = __builtin_nontemporal_load((const f32x4*)(X + o + 4)); }
;                 float ss[2] = {0.f, 0.f};
; #pragma unroll
;                 for (int q = 0; q < 4; ++q) { const int m = 2 * mh + (q >> 1), bj = q & 1; const size_t o = (size_t)(row0 + ai * 128 + m * 16) * D + col0 + bj * 128;
;                     const f32x4 h0 = x0[q] + acc[ai][bj][m][0], h1 = x1[q] + acc[ai][bj][m][1];
;                     *(f32x4*)(H + o) = h0; *(f32x4*)(H + o + 4) = h1;
;                     ss[q >> 1] += (h0.x * h0.x + h0.y * h0.y) + (h0.z * h0.z + h0.w * h0.w) + (h1.x * h1.x + h1.y * h1.y) + (h1.z * h1.z + h1.w * h1.w);
;                     const f32x4 f0 = h0 * g0[bj], f1 = h1 * g1[bj];
;                     u32x4 w; w.x = pk2(f0.x, f0.y); w.y = pk2(f0.z, f0.w); w.z = pk2(f1.x, f1.y); w.w = pk2(f1.z, f1.w);
;                     *(u32x4*)(Fu + o) = w; }
; #pragma unroll
;                 for (int mm = 0; mm < 2; ++mm) { float v = ss[mm]; v += __shfl_xor(v, 16); v += __shfl_xor(v, 32);
;                     if (fq == 0) SSP[(size_t)(row0 + ai * 128 + (2 * mh + mm) * 16) * 32 + u.pn * 4 + wc] = v; }
.LBB0_615:
	s_or_b64 exec, exec, s[20:21]
	v_or_b32_e32 v106, 32, v162
	v_ashrrev_i32_e32 v107, 31, v106
	s_waitcnt lgkmcnt(0)
	v_lshlrev_b64 v[100:101], 13, v[106:107]
	v_lshl_add_u64 v[100:101], v[164:165], 0, v[100:101]
	global_load_dwordx4 v[112:115], v[100:101], off nt
	global_load_dwordx4 v[116:119], v[100:101], off offset:16 nt
	global_load_dwordx4 v[128:131], v[100:101], off offset:528 nt
	global_load_dwordx4 v[132:135], v[100:101], off offset:512 nt
	v_or_b32_e32 v104, 48, v162
	v_ashrrev_i32_e32 v105, 31, v104
	v_lshlrev_b64 v[100:101], 13, v[104:105]
	v_lshl_add_u64 v[166:167], v[164:165], 0, v[100:101]
	global_load_dwordx4 v[136:139], v[166:167], off nt
	global_load_dwordx4 v[140:143], v[166:167], off offset:16 nt
	global_load_dwordx4 v[100:103], v[166:167], off offset:528 nt
	global_load_dwordx4 v[178:181], v[166:167], off offset:512 nt
	v_or_b32_e32 v224, 0x80, v162
	v_ashrrev_i32_e32 v225, 31, v224
	v_lshlrev_b64 v[224:225], 13, v[224:225]
	v_lshl_add_u64 v[224:225], v[164:165], 0, v[224:225]
	global_load_dword v228, v[224:225], off
	global_load_dword v228, v[224:225], off offset:512
	v_or_b32_e32 v226, 0x90, v162
	v_ashrrev_i32_e32 v227, 31, v226
	v_lshlrev_b64 v[226:227], 13, v[226:227]
	v_lshl_add_u64 v[226:227], v[164:165], 0, v[226:227]
	global_load_dword v228, v[226:227], off
	global_load_dword v228, v[226:227], off offset:512
	v_lshlrev_b64 v[182:183], 11, v[106:107]
	v_lshl_add_u64 v[182:183], v[182:183], 0, v[160:161]
	v_lshl_add_u64 v[184:185], v[182:183], 2, s[48:49]
	v_lshlrev_b64 v[182:183], 1, v[182:183]
	v_lshl_add_u64 v[188:189], s[42:43], 0, v[182:183]
	v_lshlrev_b64 v[166:167], 11, v[104:105]
	v_lshl_add_u64 v[166:167], v[166:167], 0, v[160:161]
	v_or_b32_e32 v182, 0x100, v182
	v_lshl_add_u64 v[182:183], s[42:43], 0, v[182:183]
	v_lshl_add_u64 v[186:187], v[166:167], 2, s[48:49]
	s_waitcnt vmcnt(7)
	v_pk_add_f32 v[94:95], v[94:95], v[114:115]
	v_pk_add_f32 v[92:93], v[92:93], v[112:113]
	s_waitcnt vmcnt(6)
	v_pk_add_f32 v[90:91], v[90:91], v[118:119]
	v_pk_add_f32 v[88:89], v[88:89], v[116:117]
	s_waitcnt vmcnt(4)
	v_pk_add_f32 v[86:87], v[86:87], v[134:135]
	v_pk_add_f32 v[84:85], v[84:85], v[132:133]
	v_pk_add_f32 v[80:81], v[80:81], v[128:129]
	v_mul_f32_e32 v163, v93, v93
	v_mul_f32_e32 v177, v95, v95
	v_mul_f32_e32 v190, v89, v89
	v_mul_f32_e32 v191, v91, v91
	v_pk_mul_f32 v[112:113], v[126:127], v[94:95]
	v_pk_mul_f32 v[114:115], v[124:125], v[92:93]
	v_pk_mul_f32 v[116:117], v[122:123], v[90:91]
	v_pk_mul_f32 v[118:119], v[120:121], v[88:89]
	v_mul_f32_e32 v192, v85, v85
	v_mul_f32_e32 v193, v87, v87
	v_pk_add_f32 v[82:83], v[82:83], v[130:131]
	global_store_dwordx4 v[184:185], v[92:95], off
	global_store_dwordx4 v[184:185], v[88:91], off offset:16
	v_mul_f32_e32 v194, v81, v81
	v_fmac_f32_e32 v163, v92, v92
	v_fmac_f32_e32 v177, v94, v94
	v_fmac_f32_e32 v190, v88, v88
	v_fmac_f32_e32 v191, v90, v90
	v_cvt_pk_bf16_f32 v88, v114, v115
	v_cvt_pk_bf16_f32 v89, v112, v113
	v_cvt_pk_bf16_f32 v90, v118, v119
	v_cvt_pk_bf16_f32 v91, v116, v117
	v_fmac_f32_e32 v192, v84, v84
	v_fmac_f32_e32 v193, v86, v86
	v_mul_f32_e32 v195, v83, v83
	v_pk_mul_f32 v[134:135], v[96:97], v[80:81]
	v_fmac_f32_e32 v194, v80, v80
	v_add_f32_e32 v113, v163, v177
	global_store_dwordx4 v[188:189], v[88:91], off
	global_store_dwordx4 v[184:185], v[84:87], off offset:512
	global_store_dwordx4 v[184:185], v[80:83], off offset:528
	v_fmac_f32_e32 v195, v82, v82
	s_waitcnt vmcnt(8)
	v_pk_add_f32 v[78:79], v[78:79], v[138:139]
	v_add_f32_e32 v80, v192, v193
	v_add_f32_e32 v81, v113, v190
	v_add_f32_e32 v80, v80, v194
	v_add_f32_e32 v81, v191, v81
	v_add_f32_e32 v80, v195, v80
	v_add_f32_e32 v90, v81, v80
	ds_bpermute_b32 v91, v176, v90
	v_pk_add_f32 v[76:77], v[76:77], v[136:137]
	s_waitcnt vmcnt(7)
	v_pk_add_f32 v[74:75], v[74:75], v[142:143]
	v_pk_add_f32 v[72:73], v[72:73], v[140:141]
	v_pk_mul_f32 v[128:129], v[110:111], v[86:87]
	v_pk_mul_f32 v[130:131], v[108:109], v[84:85]
	v_pk_mul_f32 v[132:133], v[98:99], v[82:83]
	v_pk_mul_f32 v[136:137], v[126:127], v[78:79]
	v_pk_mul_f32 v[138:139], v[124:125], v[76:77]
	v_pk_mul_f32 v[140:141], v[122:123], v[74:75]
	v_pk_mul_f32 v[142:143], v[120:121], v[72:73]
	v_lshlrev_b64 v[86:87], 1, v[166:167]
	v_cvt_pk_bf16_f32 v92, v130, v131
	v_cvt_pk_bf16_f32 v93, v128, v129
	v_cvt_pk_bf16_f32 v94, v134, v135
	v_cvt_pk_bf16_f32 v95, v132, v133
	v_cvt_pk_bf16_f32 v112, v138, v139
	v_cvt_pk_bf16_f32 v113, v136, v137
	v_cvt_pk_bf16_f32 v114, v142, v143
	v_cvt_pk_bf16_f32 v115, v140, v141
	v_lshl_add_u64 v[80:81], s[42:43], 0, v[86:87]
	s_waitcnt vmcnt(5)
	v_pk_add_f32 v[70:71], v[70:71], v[180:181]
	v_pk_add_f32 v[68:69], v[68:69], v[178:179]
	global_store_dwordx4 v[182:183], v[92:95], off
	global_store_dwordx4 v[186:187], v[76:79], off
	global_store_dwordx4 v[186:187], v[72:75], off offset:16
	global_store_dwordx4 v[80:81], v[112:115], off
	v_pk_mul_f32 v[80:81], v[110:111], v[70:71]
	v_pk_mul_f32 v[82:83], v[108:109], v[68:69]
	v_pk_add_f32 v[66:67], v[66:67], v[102:103]
	v_cvt_pk_bf16_f32 v82, v82, v83
	v_cvt_pk_bf16_f32 v83, v80, v81
	s_waitcnt lgkmcnt(0)
	v_add_f32_e32 v80, v90, v91
	ds_bpermute_b32 v81, v175, v80
	v_pk_add_f32 v[64:65], v[64:65], v[100:101]
	v_pk_mul_f32 v[88:89], v[98:99], v[66:67]
	v_pk_mul_f32 v[84:85], v[96:97], v[64:65]
	v_or_b32_e32 v86, 0x100, v86
	v_cvt_pk_bf16_f32 v84, v84, v85
	v_cvt_pk_bf16_f32 v85, v88, v89
	v_lshl_add_u64 v[86:87], s[42:43], 0, v[86:87]
	global_store_dwordx4 v[186:187], v[68:71], off offset:512
	global_store_dwordx4 v[186:187], v[64:67], off offset:528
	global_store_dwordx4 v[86:87], v[82:85], off
	s_and_saveexec_b64 s[20:21], s[6:7]
	s_cbranch_execz .LBB0_617
	s_waitcnt lgkmcnt(0)
	v_add_f32_e32 v82, v80, v81
	v_lshlrev_b64 v[80:81], 7, v[106:107]
	v_lshl_add_u64 v[80:81], s[18:19], 0, v[80:81]
	global_store_dword v[80:81], v82, off

; __device__ __forceinline__ unsigned pk2(float lo, float hi) { f32x2 v = {lo, hi}; bf16x2_t b = __builtin_convertvector(v, bf16x2_t); return __builtin_bit_cast(unsigned, b); }
;     __device__ __forceinline__ void operator()(const AccT& acc, const pg8::Unit& u, int wr, int wc, int fr, int fq) const {
;     ...
;             for (int mh = 0; mh < 2; ++mh) {
;                 f32x4 x0[4], x1[4];
; #pragma unroll
;                 for (int q = 0; q < 4; ++q) { const int m = 2 * mh + (q >> 1), bj = q & 1; const size_t o = (size_t)(row0 + ai * 128 + m * 16) * D + col0 + bj * 128;
;                     x0[q] = __builtin_nontemporal_load((const f32x4*)(X + o)); x1[q] = __builtin_nontemporal_load((const f32x4*)(X + o + 4)); }
;                 float ss[2] = {0.f, 0.f};
; #pragma unroll
;                 for (int q = 0; q < 4; ++q) { const int m = 2 * mh + (q >> 1), bj = q & 1; const size_t o = (size_t)(row0 + ai * 128 + m * 16) * D + col0 + bj * 128;
;                     const f32x4 h0 = x0[q] + acc[ai][bj][m][0], h1 = x1[q] + acc[ai][bj][m][1];
;                     *(f32x4*)(H + o) = h0; *(f32x4*)(H + o + 4) = h1;
;                     ss[q >> 1] += (h0.x * h0.x + h0.y * h0.y) + (h0.z * h0.z + h0.w * h0.w) + (h1.x * h1.x + h1.y * h1.y) + (h1.z * h1.z + h1.w * h1.w);
;                     const f32x4 f0 = h0 * g0[bj], f1 = h1 * g1[bj];
;                     u32x4 w; w.x = pk2(f0.x, f0.y); w.y = pk2(f0.z, f0.w); w.z = pk2(f1.x, f1.y); w.w = pk2(f1.z, f1.w);
;                     *(u32x4*)(Fu + o) = w; }
; #pragma unroll
;                 for (int mm = 0; mm < 2; ++mm) { float v = ss[mm]; v += __shfl_xor(v, 16); v += __shfl_xor(v, 32);
;                     if (fq == 0) SSP[(size_t)(row0 + ai * 128 + (2 * mh + mm) * 16) * 32 + u.pn * 4 + wc] = v; }
.LBB0_619:
	s_or_b64 exec, exec, s[20:21]
	v_add_u32_e32 v70, 0x80, v162
	v_ashrrev_i32_e32 v71, 31, v70
	s_waitcnt lgkmcnt(0)
	v_lshlrev_b64 v[64:65], 13, v[70:71]
	v_lshl_add_u64 v[64:65], v[164:165], 0, v[64:65]
	global_load_dwordx4 v[72:75], v[64:65], off nt
	global_load_dwordx4 v[76:79], v[64:65], off offset:16 nt
	global_load_dwordx4 v[80:83], v[64:65], off offset:528 nt
	global_load_dwordx4 v[84:87], v[64:65], off offset:512 nt
	v_add_u32_e32 v68, 0x90, v162
	v_ashrrev_i32_e32 v69, 31, v68
	v_lshlrev_b64 v[64:65], 13, v[68:69]
	v_lshl_add_u64 v[100:101], v[164:165], 0, v[64:65]
	global_load_dwordx4 v[88:91], v[100:101], off nt
	global_load_dwordx4 v[92:95], v[100:101], off offset:16 nt
	global_load_dwordx4 v[64:67], v[100:101], off offset:528 nt
	s_nop 0
	global_load_dwordx4 v[100:103], v[100:101], off offset:512 nt
	v_or_b32_e32 v224, 0xa0, v162
	v_ashrrev_i32_e32 v225, 31, v224
	v_lshlrev_b64 v[224:225], 13, v[224:225]
	v_lshl_add_u64 v[224:225], v[164:165], 0, v[224:225]
	global_load_dword v228, v[224:225], off
	global_load_dword v228, v[224:225], off offset:512
	v_or_b32_e32 v226, 0xb0, v162
	v_ashrrev_i32_e32 v227, 31, v226
	v_lshlrev_b64 v[226:227], 13, v[226:227]
	v_lshl_add_u64 v[226:227], v[164:165], 0, v[226:227]
	global_load_dword v228, v[226:227], off
	global_load_dword v228, v[226:227], off offset:512
	v_lshlrev_b64 v[104:105], 11, v[70:71]
	v_lshl_add_u64 v[104:105], v[104:105], 0, v[160:161]
	v_lshl_add_u64 v[112:113], v[104:105], 2, s[48:49]
	v_lshlrev_b64 v[104:105], 1, v[104:105]
	v_lshl_add_u64 v[116:117], s[42:43], 0, v[104:105]
	v_lshlrev_b64 v[106:107], 11, v[68:69]
	v_lshl_add_u64 v[106:107], v[106:107], 0, v[160:161]
	v_or_b32_e32 v104, 0x100, v104
	v_lshl_add_u64 v[104:105], s[42:43], 0, v[104:105]
	v_lshl_add_u64 v[114:115], v[106:107], 2, s[48:49]
	s_waitcnt vmcnt(7)
	v_pk_add_f32 v[62:63], v[62:63], v[74:75]
	v_pk_add_f32 v[60:61], v[60:61], v[72:73]
	s_waitcnt vmcnt(6)
	v_pk_add_f32 v[58:59], v[58:59], v[78:79]
	v_pk_add_f32 v[56:57], v[56:57], v[76:77]
	s_waitcnt vmcnt(4)
	v_pk_add_f32 v[54:55], v[54:55], v[86:87]
	v_pk_add_f32 v[52:53], v[52:53], v[84:85]
	v_pk_add_f32 v[48:49], v[48:49], v[80:81]
	v_mul_f32_e32 v118, v61, v61
	v_mul_f32_e32 v119, v63, v63
	v_mul_f32_e32 v128, v57, v57
	v_mul_f32_e32 v129, v59, v59
	v_pk_mul_f32 v[72:73], v[126:127], v[62:63]
	v_pk_mul_f32 v[74:75], v[124:125], v[60:61]
	v_pk_mul_f32 v[76:77], v[122:123], v[58:59]
	v_pk_mul_f32 v[78:79], v[120:121], v[56:57]
	v_mul_f32_e32 v130, v53, v53
	v_mul_f32_e32 v131, v55, v55
	v_pk_add_f32 v[50:51], v[50:51], v[82:83]
	global_store_dwordx4 v[112:113], v[60:63], off
	global_store_dwordx4 v[112:113], v[56:59], off offset:16
	v_mul_f32_e32 v132, v49, v49
	v_fmac_f32_e32 v118, v60, v60
	v_fmac_f32_e32 v119, v62, v62
	v_fmac_f32_e32 v128, v56, v56
	v_fmac_f32_e32 v129, v58, v58
	v_cvt_pk_bf16_f32 v56, v74, v75
	v_cvt_pk_bf16_f32 v57, v72, v73
	v_cvt_pk_bf16_f32 v58, v78, v79
	v_cvt_pk_bf16_f32 v59, v76, v77
	v_fmac_f32_e32 v130, v52, v52
	v_fmac_f32_e32 v131, v54, v54
	v_mul_f32_e32 v133, v51, v51
	v_pk_mul_f32 v[86:87], v[96:97], v[48:49]
	v_fmac_f32_e32 v132, v48, v48
	v_add_f32_e32 v73, v118, v119
	global_store_dwordx4 v[116:117], v[56:59], off
	global_store_dwordx4 v[112:113], v[52:55], off offset:512
	global_store_dwordx4 v[112:113], v[48:51], off offset:528
	v_fmac_f32_e32 v133, v50, v50
	s_waitcnt vmcnt(8)
	v_pk_add_f32 v[46:47], v[46:47], v[90:91]
	v_add_f32_e32 v48, v130, v131
	v_add_f32_e32 v49, v73, v128
	v_add_f32_e32 v48, v48, v132
	v_add_f32_e32 v49, v129, v49
	v_add_f32_e32 v48, v133, v48
	v_add_f32_e32 v58, v49, v48
	ds_bpermute_b32 v59, v176, v58
	v_pk_add_f32 v[44:45], v[44:45], v[88:89]
	s_waitcnt vmcnt(7)
	v_pk_add_f32 v[42:43], v[42:43], v[94:95]
	v_pk_add_f32 v[40:41], v[40:41], v[92:93]
	v_pk_mul_f32 v[80:81], v[110:111], v[54:55]
	v_pk_mul_f32 v[82:83], v[108:109], v[52:53]
	v_pk_mul_f32 v[84:85], v[98:99], v[50:51]
	v_pk_mul_f32 v[88:89], v[126:127], v[46:47]
	v_pk_mul_f32 v[90:91], v[124:125], v[44:45]
	v_pk_mul_f32 v[92:93], v[122:123], v[42:43]
	v_pk_mul_f32 v[94:95], v[120:121], v[40:41]
	v_lshlrev_b64 v[54:55], 1, v[106:107]
	v_cvt_pk_bf16_f32 v60, v82, v83
	v_cvt_pk_bf16_f32 v61, v80, v81
	v_cvt_pk_bf16_f32 v62, v86, v87
	v_cvt_pk_bf16_f32 v63, v84, v85
	v_cvt_pk_bf16_f32 v72, v90, v91
	v_cvt_pk_bf16_f32 v73, v88, v89
	v_cvt_pk_bf16_f32 v74, v94, v95
	v_cvt_pk_bf16_f32 v75, v92, v93
	v_lshl_add_u64 v[48:49], s[42:43], 0, v[54:55]
	s_waitcnt vmcnt(5)
	v_pk_add_f32 v[38:39], v[38:39], v[102:103]
	v_pk_add_f32 v[36:37], v[36:37], v[100:101]
	global_store_dwordx4 v[104:105], v[60:63], off
	global_store_dwordx4 v[114:115], v[44:47], off
	global_store_dwordx4 v[114:115], v[40:43], off offset:16
	global_store_dwordx4 v[48:49], v[72:75], off
	v_pk_mul_f32 v[48:49], v[110:111], v[38:39]
	v_pk_mul_f32 v[50:51], v[108:109], v[36:37]
	v_pk_add_f32 v[34:35], v[34:35], v[66:67]
	v_cvt_pk_bf16_f32 v50, v50, v51
	v_cvt_pk_bf16_f32 v51, v48, v49
	s_waitcnt lgkmcnt(0)
	v_add_f32_e32 v48, v58, v59
	ds_bpermute_b32 v49, v175, v48
	v_pk_add_f32 v[32:33], v[32:33], v[64:65]
	v_pk_mul_f32 v[56:57], v[98:99], v[34:35]
	v_pk_mul_f32 v[52:53], v[96:97], v[32:33]
	v_or_b32_e32 v54, 0x100, v54
	v_cvt_pk_bf16_f32 v52, v52, v53
	v_cvt_pk_bf16_f32 v53, v56, v57
	v_lshl_add_u64 v[54:55], s[42:43], 0, v[54:55]
	global_store_dwordx4 v[114:115], v[36:39], off offset:512
	global_store_dwordx4 v[114:115], v[32:35], off offset:528
	global_store_dwordx4 v[54:55], v[50:53], off
	s_and_saveexec_b64 s[20:21], s[6:7]
	s_cbranch_execz .LBB0_621
	s_waitcnt lgkmcnt(0)
	v_add_f32_e32 v50, v48, v49
	v_lshlrev_b64 v[48:49], 7, v[70:71]
	v_lshl_add_u64 v[48:49], s[18:19], 0, v[48:49]
	global_store_dword v[48:49], v50, off
